# DeltaNet chunk scan: all 12 next-chunk prefetch loads issued after the batched LDS fragment reads (none before the barrier)
# speedup vs baseline: 1.0012x; 1.0012x over previous
.LBB0_286:
	v_add_u32_e32 v101, v43, v107
	s_add_u32 s18, s94, s10
	s_waitcnt lgkmcnt(0)
	s_barrier
	s_waitcnt vmcnt(4)
	v_perm_b32 v99, v147, v103, s78
	v_perm_b32 v97, v146, v105, s78
	ds_write_b128 v76, v[2:5]
	ds_write_b128 v101, v[6:9] offset:34816
	ds_write_b128 v76, v[10:13] offset:53248
	ds_write_b128 v78, v[14:17]
	ds_write_b128 v145, v[18:21] offset:34816
	ds_write_b128 v78, v[22:25] offset:53248
	ds_write_b128 v129, v[26:29]
	v_lshl_add_u64 v[2:3], s[94:95], 0, v[108:109]
	v_lshl_add_u64 v[6:7], s[94:95], 0, v[110:111]
	v_lshl_add_u64 v[10:11], s[94:95], 0, v[126:127]
	v_lshl_add_u64 v[14:15], s[94:95], 0, v[114:115]
	v_lshl_add_u64 v[18:19], s[94:95], 0, v[116:117]
	v_lshl_add_u64 v[22:23], s[94:95], 0, v[124:125]
	v_lshl_add_u64 v[26:27], s[94:95], 0, v[120:121]
	v_lshl_add_u64 v[146:147], s[94:95], 0, v[122:123]
	v_lshl_add_u64 v[148:149], s[94:95], 0, v[118:119]
	s_addc_u32 s19, s95, s12
	v_mov_b32_e32 v128, v106
	v_pk_mul_f32 v[32:33], v[32:33], v[128:129] op_sel_hi:[1,0]
	v_pk_mul_f32 v[30:31], v[30:31], v[128:129] op_sel_hi:[1,0]
	v_pk_mul_f32 v[36:37], v[36:37], v[128:129] op_sel_hi:[1,0]
	v_pk_mul_f32 v[34:35], v[34:35], v[128:129] op_sel_hi:[1,0]
	s_add_u32 s10, s10, 4
	s_addc_u32 s12, s12, 0
	s_add_i32 s8, s8, -1
	s_nop 0
	s_waitcnt lgkmcnt(0)
	s_barrier
	ds_read_b128 v[180:183], v130
	ds_read_b128 v[196:199], v131 offset:53248
	ds_read_b128 v[184:187], v130 offset:64
	ds_read_b128 v[200:203], v131 offset:53312
	ds_read_b128 v[188:191], v130 offset:128
	ds_read_b128 v[208:211], v131 offset:53376
	ds_read_b128 v[192:195], v130 offset:192
	ds_read_b128 v[212:215], v131 offset:53440
	ds_read_b128 v[216:219], v131
	ds_read_b128 v[220:223], v131 offset:64
	ds_read_b128 v[224:227], v131 offset:128
	ds_read_b128 v[228:231], v131 offset:192
	global_load_dwordx4 v[2:5], v[2:3], off
	global_load_dwordx4 v[6:9], v[6:7], off
	global_load_dwordx4 v[10:13], v[10:11], off
	global_load_dwordx4 v[14:17], v[14:15], off
	global_load_dwordx4 v[18:21], v[18:19], off
	global_load_dwordx4 v[22:25], v[22:23], off
	global_load_dwordx4 v[26:29], v[26:27], off
	global_load_ushort v103, v[146:147], off
	global_load_ushort v147, v[148:149], off offset:-256
	global_load_ushort v105, v[148:149], off
	global_load_ushort v146, v[148:149], off offset:256
	global_load_dword v106, v1, s[18:19]
	v_lshl_add_u64 v[108:109], v[108:109], 0, s[56:57]
	v_lshl_add_u64 v[110:111], v[110:111], 0, s[56:57]
	v_lshl_add_u64 v[114:115], v[114:115], 0, s[56:57]
	s_waitcnt lgkmcnt(10)
	v_mfma_f32_16x16x32_bf16 v[152:155], v[196:199], v[180:183], 0
	ds_read_b128 v[232:235], v133
	v_lshl_add_u64 v[116:117], v[116:117], 0, s[56:57]
	s_waitcnt lgkmcnt(9)
	v_mfma_f32_16x16x32_bf16 v[152:155], v[200:203], v[184:187], v[152:155]
	ds_read_b128 v[236:239], v133 offset:64
	v_lshl_add_u64 v[118:119], v[118:119], 0, s[4:5]
	s_waitcnt lgkmcnt(8)
	v_mfma_f32_16x16x32_bf16 v[152:155], v[208:211], v[188:191], v[152:155]
	ds_read_b128 v[240:243], v135 offset:34816
	v_lshl_add_u64 v[120:121], v[120:121], 0, s[56:57]
	s_waitcnt lgkmcnt(7)
	v_mfma_f32_16x16x32_bf16 v[152:155], v[212:215], v[192:195], v[152:155]
	ds_read_b128 v[176:179], v135 offset:34880
	v_lshl_add_u64 v[122:123], v[122:123], 0, s[4:5]
	s_waitcnt lgkmcnt(7)
	v_mfma_f32_16x16x32_bf16 v[148:151], v[216:219], v[180:183], 0
	v_lshl_add_u64 v[124:125], v[124:125], 0, s[4:5]
	s_waitcnt lgkmcnt(6)
	v_mfma_f32_16x16x32_bf16 v[148:151], v[220:223], v[184:187], v[148:151]
	v_lshl_add_u64 v[126:127], v[126:127], 0, s[4:5]
	s_waitcnt lgkmcnt(5)
	v_mfma_f32_16x16x32_bf16 v[148:151], v[224:227], v[188:191], v[148:151]
	v_and_b32_e32 v157, 0xffff0000, v99
	s_waitcnt lgkmcnt(4)
	v_mfma_f32_16x16x32_bf16 v[148:151], v[228:231], v[192:195], v[148:151]
	v_lshlrev_b32_e32 v156, 16, v99
	v_and_b32_e32 v159, 0xffff0000, v97
	v_lshlrev_b32_e32 v158, 16, v97
	v_pk_add_f32 v[152:153], v[156:157], v[152:153] neg_lo:[0,1] neg_hi:[0,1]
	v_pk_add_f32 v[154:155], v[158:159], v[154:155] neg_lo:[0,1] neg_hi:[0,1]
	v_cvt_pk_bf16_f32 v152, v152, v153
	v_cvt_pk_bf16_f32 v153, v154, v155
	ds_write_b64 v132, v[152:153]
	s_waitcnt lgkmcnt(0)
	s_barrier
	ds_read_b128 v[180:183], v134
	ds_read_b128 v[184:187], v134 offset:64
	ds_read_b128 v[188:191], v136
	ds_read_b128 v[192:195], v136 offset:64
	ds_read_b128 v[196:199], v136 offset:2304
	ds_read_b128 v[200:203], v136 offset:2368
	s_waitcnt lgkmcnt(5)
	v_mfma_f32_16x16x32_bf16 v[148:151], v[232:235], v[180:183], v[148:151]
	v_lshl_add_u64 v[152:153], s[94:95], 0, v[112:113]
	s_waitcnt lgkmcnt(4)
	v_mfma_f32_16x16x32_bf16 v[148:151], v[236:239], v[184:187], v[148:151]
	v_lshl_add_u64 v[112:113], v[112:113], 0, s[4:5]
	s_waitcnt lgkmcnt(3)
	v_mfma_f32_16x16x32_bf16 v[30:33], v[240:243], v[188:191], v[30:33]
	s_waitcnt lgkmcnt(2)
	v_mfma_f32_16x16x32_bf16 v[30:33], v[176:179], v[192:195], v[30:33]
	s_waitcnt lgkmcnt(1)
	v_mfma_f32_16x16x32_bf16 v[34:37], v[240:243], v[196:199], v[34:37]
	s_waitcnt lgkmcnt(0)
	v_mfma_f32_16x16x32_bf16 v[34:37], v[176:179], v[200:203], v[34:37]
	s_nop 0
	v_cvt_pk_bf16_f32 v97, v148, s0
	global_store_short v[152:153], v97, off offset:-512
	v_cvt_pk_bf16_f32 v97, v149, s0
	global_store_short v[152:153], v97, off offset:-256
	v_cvt_pk_bf16_f32 v97, v150, s0
	global_store_short v[152:153], v97, off
	v_cvt_pk_bf16_f32 v97, v151, s0
	global_store_short v[152:153], v97, off offset:256
	v_cvt_pk_bf16_f32 v156, v30, v31
	v_cvt_pk_bf16_f32 v157, v32, v33
	ds_write_b64 v137, v[156:157]
	v_cvt_pk_bf16_f32 v158, v34, v35
	v_cvt_pk_bf16_f32 v159, v36, v37
	ds_write_b64 v137, v[158:159] offset:4352
	s_cmp_eq_u32 s8, 0
	s_cbranch_scc0 .LBB0_286
	s_waitcnt lgkmcnt(0)
	s_barrier
	s_waitcnt vmcnt(4)
	ds_write_b128 v76, v[2:5]
	ds_write_b128 v101, v[6:9] offset:34816
	ds_write_b128 v76, v[10:13] offset:53248
	ds_write_b128 v78, v[14:17]
	ds_write_b128 v145, v[18:21] offset:34816
	ds_write_b128 v78, v[22:25] offset:53248
	ds_write_b128 v129, v[26:29]
	s_waitcnt lgkmcnt(0)
	s_barrier
	ds_read_b128 v[2:5], v131 offset:53248
	ds_read_b128 v[6:9], v130
	ds_read_b128 v[10:13], v130 offset:64
	ds_read_b128 v[14:17], v131 offset:53312
	s_waitcnt lgkmcnt(2)
	v_mfma_f32_16x16x32_bf16 v[2:5], v[2:5], v[6:9], 0
	ds_read_b128 v[18:21], v131
	ds_read_b128 v[22:25], v131 offset:64
	v_lshlrev_b32_e32 v27, 16, v147
	v_lshlrev_b32_e32 v26, 16, v103
	s_waitcnt lgkmcnt(2)
	v_mfma_f32_16x16x32_bf16 v[2:5], v[14:17], v[10:13], v[2:5]
	ds_read_b128 v[14:17], v131 offset:53376
	s_lshl_b32 s8, s11, 1
	s_add_u32 s6, s6, s8
	s_waitcnt lgkmcnt(2)
	v_mfma_f32_16x16x32_bf16 v[6:9], v[18:21], v[6:9], 0
	s_addc_u32 s7, s7, 0
	s_add_i32 s2, s2, s50
	s_cmpk_gt_i32 s2, 0xff
	s_waitcnt lgkmcnt(1)
	v_mfma_f32_16x16x32_bf16 v[6:9], v[22:25], v[10:13], v[6:9]
	ds_read_b128 v[10:13], v131 offset:53440
	ds_read_b128 v[18:21], v130 offset:128
	ds_read_b128 v[22:25], v130 offset:192
	s_waitcnt lgkmcnt(1)
	v_mfma_f32_16x16x32_bf16 v[2:5], v[14:17], v[18:21], v[2:5]
	s_waitcnt lgkmcnt(0)
	v_mfma_f32_16x16x32_bf16 v[2:5], v[10:13], v[22:25], v[2:5]
	ds_read_b128 v[10:13], v131 offset:128
	ds_read_b128 v[14:17], v131 offset:192
	s_waitcnt lgkmcnt(1)
	v_mfma_f32_16x16x32_bf16 v[6:9], v[10:13], v[18:21], v[6:9]
	s_nop 3
	v_add_f32_e64 v2, v26, -v2
	v_add_f32_e64 v3, v27, -v3
	v_lshlrev_b32_e32 v27, 16, v146
	v_lshlrev_b32_e32 v26, 16, v105
	v_pk_add_f32 v[4:5], v[26:27], v[4:5] neg_lo:[0,1] neg_hi:[0,1]
	v_cvt_pk_bf16_f32 v2, v2, v3
	v_cvt_pk_bf16_f32 v3, v4, v5
	ds_write_b64 v132, v[2:3]
	s_waitcnt lgkmcnt(0)
	s_barrier
	ds_read_b128 v[2:5], v133
	ds_read_b128 v[10:13], v134
	ds_read_b128 v[18:21], v133 offset:64
	v_mfma_f32_16x16x32_bf16 v[6:9], v[14:17], v[22:25], v[6:9]
	ds_read_b128 v[14:17], v134 offset:64
	v_mov_b32_e32 v105, v1
	s_waitcnt lgkmcnt(2)
	v_mfma_f32_16x16x32_bf16 v[2:5], v[2:5], v[10:13], v[6:9]
	s_nop 3
	v_lshl_add_u64 v[6:7], s[6:7], 0, v[0:1]
	v_lshl_add_u64 v[6:7], v[6:7], 0, v[104:105]
	s_waitcnt lgkmcnt(0)
	v_mfma_f32_16x16x32_bf16 v[2:5], v[18:21], v[14:17], v[2:5]
	s_mov_b64 s[6:7], 0xfc000
	v_lshl_add_u64 v[108:109], v[6:7], 0, s[6:7]
	v_lshl_add_u64 v[6:7], v[66:67], 1, v[108:109]
	s_waitcnt vmcnt(4)
	v_pk_mul_f32 v[20:21], v[106:107], v[32:33] op_sel_hi:[0,1]
	v_pk_mul_f32 v[18:19], v[106:107], v[30:31] op_sel_hi:[0,1]
	s_nop 1
	v_cvt_pk_bf16_f32 v2, v2, s0
	global_store_short v[6:7], v2, off
	ds_read_b128 v[6:9], v135 offset:34816
	v_cvt_pk_bf16_f32 v10, v3, s0
	v_lshl_add_u64 v[2:3], v[70:71], 1, v[108:109]
	global_store_short v[2:3], v10, off
	ds_read_b128 v[10:13], v135 offset:34880
	ds_read_b128 v[14:17], v136
	ds_read_b128 v[22:25], v136 offset:64
	s_waitcnt lgkmcnt(1)
	v_mfma_f32_16x16x32_bf16 v[14:17], v[6:9], v[14:17], v[18:21]
	s_nop 2
	ds_read_b128 v[18:21], v136 offset:2304
	ds_read_b128 v[26:29], v136 offset:2368
	v_cvt_pk_bf16_f32 v4, v4, s0
	s_waitcnt lgkmcnt(2)
	v_mfma_f32_16x16x32_bf16 v[14:17], v[10:13], v[22:25], v[14:17]
	v_mul_f32_e64 v24, v106, v36
	v_mul_f32_e64 v25, v106, v37
	v_pk_mul_f32 v[22:23], v[106:107], v[34:35] op_sel_hi:[0,1]
	v_lshl_add_u64 v[2:3], v[72:73], 1, v[108:109]
	global_store_short v[2:3], v4, off
	s_waitcnt lgkmcnt(1)
	v_mfma_f32_16x16x32_bf16 v[6:9], v[6:9], v[18:21], v[22:25]
	v_cvt_pk_bf16_f32 v4, v5, s0
	v_lshl_add_u64 v[2:3], v[74:75], 1, v[108:109]
	global_store_short v[2:3], v4, off
	s_waitcnt lgkmcnt(0)
	v_mfma_f32_16x16x32_bf16 v[2:5], v[10:13], v[26:29], v[6:9]
	s_nop 2
	v_cvt_pk_bf16_f32 v6, v14, v15
	v_cvt_pk_bf16_f32 v7, v16, v17
	s_nop 2
	v_cvt_pk_bf16_f32 v2, v2, v3
	v_cvt_pk_bf16_f32 v3, v4, v5
	ds_write_b64 v137, v[6:7]
	ds_write_b64 v137, v[2:3] offset:4352
	s_cbranch_scc0 .LBB0_282
